# fin phase: GLU weight staging to LDS as 2 batches of 8 loads instead of 16 serialized load-wait-write round trips
# speedup vs baseline: 1.0378x; 1.0026x over previous
; __device__ __forceinline__ void phase_fin(const Params& p, int l, int Mrows, char* smem) {
;     ...
;   __syncthreads();
;   for (int e = tid; e < 256 * 32; e += NT) {
;     const int n = e >> 5, c8 = (e & 31) * 8;
;     *reinterpret_cast<uint4*>(Gs + n * 264 + c8) = *reinterpret_cast<const uint4*>(GluT + (size_t)n * 256 + c8);
;   }
.LBB0_1337:
	s_or_b64 exec, exec, s[0:1]
	s_waitcnt lgkmcnt(0)
	v_mov_b32_e32 v2, v176
	s_movk_i32 s0, 0x2000
	s_barrier
	s_nop 0
	v_cmp_gt_i32_e32 vcc, s0, v2
	s_barrier
	s_and_saveexec_b64 s[0:1], vcc
	s_cbranch_execz .LBB0_1340
	v_readlane_b32 s2, v255, 29
	s_add_u32 s4, s2, 0x2100000
	v_readlane_b32 s2, v255, 30
	s_addc_u32 s5, s2, 0
	v_ashrrev_i32_e32 v4, 5, v2
	v_lshlrev_b32_e32 v5, 4, v2
	v_and_b32_e32 v5, 0x1f0, v5
	v_lshl_add_u32 v6, v4, 9, v5
	v_mul_lo_u32 v4, v4, s21
	v_add_u32_e32 v8, v4, v5
	v_add_u32_e32 v9, 0x10800, v8
	global_load_dwordx4 v[140:143], v6, s[4:5]
	v_add_u32_e32 v173, 0x2000, v6
	global_load_dwordx4 v[144:147], v173, s[4:5]
	v_add_u32_e32 v174, 0x4000, v6
	global_load_dwordx4 v[148:151], v174, s[4:5]
	v_add_u32_e32 v175, 0x6000, v6
	global_load_dwordx4 v[152:155], v175, s[4:5]
	v_add_u32_e32 v172, 0x8000, v6
	global_load_dwordx4 v[156:159], v172, s[4:5]
	v_add_u32_e32 v173, 0xa000, v6
	global_load_dwordx4 v[160:163], v173, s[4:5]
	v_add_u32_e32 v174, 0xc000, v6
	global_load_dwordx4 v[164:167], v174, s[4:5]
	v_add_u32_e32 v175, 0xe000, v6
	global_load_dwordx4 v[168:171], v175, s[4:5]
	s_waitcnt vmcnt(0)
	ds_write_b128 v8, v[140:143]
	ds_write_b128 v8, v[144:147] offset:8448
	ds_write_b128 v8, v[148:151] offset:16896
	ds_write_b128 v8, v[152:155] offset:25344
	ds_write_b128 v8, v[156:159] offset:33792
	ds_write_b128 v8, v[160:163] offset:42240
	ds_write_b128 v8, v[164:167] offset:50688
	ds_write_b128 v8, v[168:171] offset:59136
	v_add_u32_e32 v172, 0x10000, v6
	global_load_dwordx4 v[140:143], v172, s[4:5]
	v_add_u32_e32 v173, 0x12000, v6
	global_load_dwordx4 v[144:147], v173, s[4:5]
	v_add_u32_e32 v174, 0x14000, v6
	global_load_dwordx4 v[148:151], v174, s[4:5]
	v_add_u32_e32 v175, 0x16000, v6
	global_load_dwordx4 v[152:155], v175, s[4:5]
	v_add_u32_e32 v172, 0x18000, v6
	global_load_dwordx4 v[156:159], v172, s[4:5]
	v_add_u32_e32 v173, 0x1a000, v6
	global_load_dwordx4 v[160:163], v173, s[4:5]
	v_add_u32_e32 v174, 0x1c000, v6
	global_load_dwordx4 v[164:167], v174, s[4:5]
	v_add_u32_e32 v175, 0x1e000, v6
	global_load_dwordx4 v[168:171], v175, s[4:5]
	s_waitcnt vmcnt(0)
	ds_write_b128 v9, v[140:143]
	ds_write_b128 v9, v[144:147] offset:8448
	ds_write_b128 v9, v[148:151] offset:16896
	ds_write_b128 v9, v[152:155] offset:25344
	ds_write_b128 v9, v[156:159] offset:33792
	ds_write_b128 v9, v[160:163] offset:42240
	ds_write_b128 v9, v[164:167] offset:50688
	ds_write_b128 v9, v[168:171] offset:59136
